# v19 + phase_init: four rows per trip with all loads requested before first use (wave-uniform scalar row math), was one HBM round trip per row
# speedup vs baseline: 1.0267x; 1.0005x over previous
.LBB0_357:
.LBB0_358:
	v_readlane_b32 s0, v251, 52
	s_mov_b32 s1, s80
	v_mbcnt_lo_u32_b32 v2, -1, 0
	v_mbcnt_hi_u32_b32 v2, -1, v2
	s_lshl_b32 s0, s0, 6
	s_lshl_b32 s1, s80, 9
	s_add_i32 s0, s0, s1
	v_add_u32_e32 v8, s0, v2
	s_mov_b32 s0, 0x800000
	v_writelane_b32 v251, s1, 55
	v_cmp_gt_i32_e32 vcc, s0, v8
	s_and_saveexec_b64 s[2:3], vcc
	s_cbranch_execz .LBB0_365
	s_lshl_b32 s8, s54, 9
	v_lshlrev_b32_e32 v9, 2, v8
	s_lshl_b32 s9, s54, 11
	s_mov_b64 s[6:7], 0
	s_movk_i32 s10, 0x4000
	s_movk_i32 s11, 0x3fff
	v_mov_b32_e32 v3, 0
	s_movk_i32 s12, 0x1000
	s_mov_b32 s13, 0x7fffff
	s_mov_b64 s[0:1], exec
	s_cmp_lg_u64 s[0:1], -1
	s_cbranch_scc1 .Linit_slow
	v_readlane_b32 s100, v251, 52
	v_readlane_b32 s48, v251, 2
	v_readlane_b32 s49, v251, 3
	v_readlane_b32 s50, v251, 4
	v_readlane_b32 s51, v251, 5
	s_nop 4
	s_lshl_b32 s100, s100, 6
	s_lshl_b32 s101, s80, 9
	s_add_i32 s100, s100, s101
	v_and_b32_e32 v112, 0xff, v8
	v_lshlrev_b32_e32 v113, 3, v112
	v_lshlrev_b32_e32 v112, 4, v112
	v_add_u32_e32 v114, 0x1000, v112
.Linit_group:
	s_mul_i32 s1, s8, 3
	s_add_i32 s1, s1, s100
	s_add_i32 s1, s1, 63
	s_cmp_lt_u32 s1, 0x800000
	s_cbranch_scc0 .Linit_rest
	s_lshr_b32 s0, s100, 8
	s_lshl_b32 s4, s0, 11
	s_add_u32 s36, s24, s4
	s_addc_u32 s37, s25, 0
	s_cmp_lt_u32 s0, 0x4000
	s_cbranch_scc1 .Linit_p0
	s_sub_i32 s1, s0, 0x4000
	s_lshr_b32 s5, s1, 12
	s_add_i32 s5, s5, 2
	s_lshl_b32 s1, s1, 12
	s_add_u32 s44, s50, s1
	s_addc_u32 s45, s51, 0
	s_branch .Linit_q0
.Linit_p0:
	s_lshr_b32 s5, s0, 13
	s_lshl_b32 s1, s0, 12
	s_add_u32 s44, s48, s1
	s_addc_u32 s45, s49, 0
.Linit_q0:
	s_mul_i32 s5, s5, 0x9000
	s_add_u32 s46, s92, s5
	s_addc_u32 s47, s93, 0
	global_load_dwordx4 v[68:71], v112, s[46:47]
	global_load_dwordx4 v[72:75], v114, s[46:47]
	global_load_dwordx4 v[64:67], v112, s[44:45]
	s_mul_i32 s0, s8, 1
	s_add_i32 s0, s0, s100
	s_lshr_b32 s0, s0, 8
	s_lshl_b32 s4, s0, 11
	s_add_u32 s38, s24, s4
	s_addc_u32 s39, s25, 0
	s_cmp_lt_u32 s0, 0x4000
	s_cbranch_scc1 .Linit_p1
	s_sub_i32 s1, s0, 0x4000
	s_lshr_b32 s5, s1, 12
	s_add_i32 s5, s5, 2
	s_lshl_b32 s1, s1, 12
	s_add_u32 s44, s50, s1
	s_addc_u32 s45, s51, 0
	s_branch .Linit_q1

.Linit_q1:
	s_mul_i32 s5, s5, 0x9000
	s_add_u32 s46, s92, s5
	s_addc_u32 s47, s93, 0
	global_load_dwordx4 v[80:83], v112, s[46:47]
	global_load_dwordx4 v[84:87], v114, s[46:47]
	global_load_dwordx4 v[76:79], v112, s[44:45]
	s_mul_i32 s0, s8, 2
	s_add_i32 s0, s0, s100
	s_lshr_b32 s0, s0, 8
	s_lshl_b32 s4, s0, 11
	s_add_u32 s40, s24, s4
	s_addc_u32 s41, s25, 0
	s_cmp_lt_u32 s0, 0x4000
	s_cbranch_scc1 .Linit_p2
	s_sub_i32 s1, s0, 0x4000
	s_lshr_b32 s5, s1, 12
	s_add_i32 s5, s5, 2
	s_lshl_b32 s1, s1, 12
	s_add_u32 s44, s50, s1
	s_addc_u32 s45, s51, 0
	s_branch .Linit_q2

.Linit_q2:
	s_mul_i32 s5, s5, 0x9000
	s_add_u32 s46, s92, s5
	s_addc_u32 s47, s93, 0
	global_load_dwordx4 v[92:95], v112, s[46:47]
	global_load_dwordx4 v[96:99], v114, s[46:47]
	global_load_dwordx4 v[88:91], v112, s[44:45]
	s_mul_i32 s0, s8, 3
	s_add_i32 s0, s0, s100
	s_lshr_b32 s0, s0, 8
	s_lshl_b32 s4, s0, 11
	s_add_u32 s42, s24, s4
	s_addc_u32 s43, s25, 0
	s_cmp_lt_u32 s0, 0x4000
	s_cbranch_scc1 .Linit_p3
	s_sub_i32 s1, s0, 0x4000
	s_lshr_b32 s5, s1, 12
	s_add_i32 s5, s5, 2
	s_lshl_b32 s1, s1, 12
	s_add_u32 s44, s50, s1
	s_addc_u32 s45, s51, 0
	s_branch .Linit_q3

.Linit_q3:
	s_mul_i32 s5, s5, 0x9000
	s_add_u32 s46, s92, s5
	s_addc_u32 s47, s93, 0
	global_load_dwordx4 v[104:107], v112, s[46:47]
	global_load_dwordx4 v[108:111], v114, s[46:47]
	global_load_dwordx4 v[100:103], v112, s[44:45]
	s_waitcnt vmcnt(9)
	v_pk_add_f32 v[72:73], v[72:73], 1.0 op_sel_hi:[1,0]
	v_pk_add_f32 v[74:75], v[74:75], 1.0 op_sel_hi:[1,0]
	v_pk_fma_f32 v[68:69], v[64:65], v[72:73], v[68:69]
	v_pk_fma_f32 v[70:71], v[66:67], v[74:75], v[70:71]
	v_cvt_pk_bf16_f32 v64, v68, v69
	v_cvt_pk_bf16_f32 v65, v70, v71
	global_store_dwordx2 v113, v[64:65], s[36:37]
	s_waitcnt vmcnt(7)
	v_pk_add_f32 v[84:85], v[84:85], 1.0 op_sel_hi:[1,0]
	v_pk_add_f32 v[86:87], v[86:87], 1.0 op_sel_hi:[1,0]
	v_pk_fma_f32 v[80:81], v[76:77], v[84:85], v[80:81]
	v_pk_fma_f32 v[82:83], v[78:79], v[86:87], v[82:83]
	v_cvt_pk_bf16_f32 v76, v80, v81
	v_cvt_pk_bf16_f32 v77, v82, v83
	global_store_dwordx2 v113, v[76:77], s[38:39]
	s_waitcnt vmcnt(5)
	v_pk_add_f32 v[96:97], v[96:97], 1.0 op_sel_hi:[1,0]
	v_pk_add_f32 v[98:99], v[98:99], 1.0 op_sel_hi:[1,0]
	v_pk_fma_f32 v[92:93], v[88:89], v[96:97], v[92:93]
	v_pk_fma_f32 v[94:95], v[90:91], v[98:99], v[94:95]
	v_cvt_pk_bf16_f32 v88, v92, v93
	v_cvt_pk_bf16_f32 v89, v94, v95
	global_store_dwordx2 v113, v[88:89], s[40:41]
	s_waitcnt vmcnt(3)
	v_pk_add_f32 v[108:109], v[108:109], 1.0 op_sel_hi:[1,0]
	v_pk_add_f32 v[110:111], v[110:111], 1.0 op_sel_hi:[1,0]
	v_pk_fma_f32 v[104:105], v[100:101], v[108:109], v[104:105]
	v_pk_fma_f32 v[106:107], v[102:103], v[110:111], v[106:107]
	v_cvt_pk_bf16_f32 v100, v104, v105
	v_cvt_pk_bf16_f32 v101, v106, v107
	global_store_dwordx2 v113, v[100:101], s[42:43]
	s_lshl_b32 s0, s8, 2
	s_add_i32 s100, s100, s0
	v_add_u32_e32 v8, s0, v8
	s_lshl_b32 s0, s9, 2
	v_add_u32_e32 v9, s0, v9
	s_branch .Linit_group
.Linit_rest:
	s_cmp_lt_u32 s100, 0x800000
	s_cbranch_scc0 .LBB0_365
.Linit_slow:
	s_branch .LBB0_361
.LBB0_360:
	s_or_b64 exec, exec, s[0:1]
	v_lshrrev_b32_e32 v2, 12, v2
	v_ashrrev_i32_e32 v10, 21, v8
	v_add_u32_e32 v2, 2, v2
	v_cndmask_b32_e32 v10, v2, v10, vcc
	v_mul_i32_i24_e32 v10, 9, v10
	v_ashrrev_i32_e32 v11, 31, v10
	v_and_b32_e32 v22, 0x3fc, v9
	v_lshlrev_b64 v[10:11], 12, v[10:11]
	v_lshlrev_b32_e32 v2, 2, v22
	v_lshl_add_u64 v[10:11], s[92:93], 0, v[10:11]
	v_lshl_add_u64 v[10:11], v[10:11], 0, v[2:3]
	v_add_co_u32_e32 v14, vcc, s12, v10
	v_lshl_add_u64 v[6:7], v[6:7], 0, v[2:3]
	s_nop 0
	v_addc_co_u32_e32 v15, vcc, 0, v11, vcc
	global_load_dwordx4 v[10:13], v[10:11], off
	s_nop 0
	global_load_dwordx4 v[14:17], v[14:15], off
	v_lshlrev_b64 v[4:5], 11, v[4:5]
	global_load_dwordx4 v[18:21], v[6:7], off
	v_add_u32_e32 v8, s8, v8
	v_lshl_add_u64 v[4:5], s[24:25], 0, v[4:5]
	v_cmp_lt_i32_e32 vcc, s13, v8
	v_lshlrev_b32_e32 v2, 1, v22
	s_or_b64 s[6:7], vcc, s[6:7]
	v_lshl_add_u64 v[4:5], v[4:5], 0, v[2:3]
	v_add_u32_e32 v9, s9, v9
	s_waitcnt vmcnt(1)
	v_pk_add_f32 v[14:15], v[14:15], 1.0 op_sel_hi:[1,0]
	v_pk_add_f32 v[6:7], v[16:17], 1.0 op_sel_hi:[1,0]
	s_waitcnt vmcnt(0)
	v_pk_fma_f32 v[10:11], v[18:19], v[14:15], v[10:11]
	v_pk_fma_f32 v[6:7], v[20:21], v[6:7], v[12:13]
	v_cvt_pk_bf16_f32 v10, v10, v11
	s_nop 0
	v_cvt_pk_bf16_f32 v11, v6, v7
	global_store_dwordx2 v[4:5], v[10:11], off
	s_andn2_b64 exec, exec, s[6:7]
	s_cbranch_execz .LBB0_365
